# decode stream: v_cvt_pk_bf16_f32 replaces the integer RNE bit trick (48 sites), score-MFMA LDS reads pipelined three steps ahead
# speedup vs baseline: 1.0070x; 1.0070x over previous
; DEV unsigned pk2(float lo, float hi) { return (unsigned)f2bf(lo) | ((unsigned)f2bf(hi) << 16); }
; DEV void lds_barrier() { asm volatile("s_waitcnt lgkmcnt(0)" ::: "memory"); __builtin_amdgcn_s_barrier(); asm volatile("" ::: "memory"); }
; #define LAS __attribute__((address_space(3)))
; DEV void sample_attn_task(int l, int item, int t, LAS unsigned char* sm, unsigned char* ws, const float* cache_ckv, const float* cache_kr, const int* page_table, const float* w_uv) {
;     ...
;       for (int pg = 0; pg < 2; ++pg) {
; #pragma unroll
;         for (int i = 0; i < 8; ++i) { const int e = t + 512 * i, key = e >> 5, c4 = e & 31; const f32x4 v = pk[8 * pg + i]; u32x2 w; w.x = pk2(v[0], v[1]); w.y = pk2(v[2], v[3]); *(LAS u32x2*)(KB + (128 * pg + key) * KST + 4 * c4) = w; }
; #pragma unroll
;         for (int i = 0; i < 2; ++i) { const int e = t + 512 * i, key = e >> 3, c4 = e & 7; const f32x4 v = pr[2 * pg + i]; u32x2 w; w.x = pk2(v[0], v[1]); w.y = pk2(v[2], v[3]); *(LAS u32x2*)(KB + (128 * pg + key) * KST + 128 + 4 * c4) = w; }
;         LOAD_PAGE(pg, 2 * it + pg + 2);
;         lds_barrier();
;         if ((wv >> 2) == pg) {
;         f32x16 S;
; #pragma unroll
;         for (int r = 0; r < 16; ++r) S[r] = 0.f;
;         const LAS bf16_t* kr_ = KB + (32 * wv + r32) * KST + 8 * hi;
; #pragma unroll
;         for (int s2 = 0; s2 < 10; ++s2) S = __builtin_amdgcn_mfma_f32_32x32x16_bf16(*(const LAS bf16x8*)(kr_ + 16 * s2), *(const LAS bf16x8*)(QB + r32 * KST + 8 * hi + 16 * s2), S, 0, 0, 0);
.LBB0_1394:
	s_waitcnt vmcnt(19)
	v_cvt_pk_bf16_f32 v2, v168, v169
	v_cvt_pk_bf16_f32 v3, v170, v171
	s_waitcnt vmcnt(18)
	ds_write_b64 v193, v[2:3]
	v_cvt_pk_bf16_f32 v2, v164, v165
	v_cvt_pk_bf16_f32 v3, v166, v167
	s_waitcnt vmcnt(17)
	ds_write_b64 v194, v[2:3]
	v_cvt_pk_bf16_f32 v2, v156, v157
	v_cvt_pk_bf16_f32 v3, v158, v159
	s_waitcnt vmcnt(16)
	ds_write_b64 v195, v[2:3]
	v_cvt_pk_bf16_f32 v2, v148, v149
	v_cvt_pk_bf16_f32 v3, v150, v151
	s_waitcnt vmcnt(15)
	ds_write_b64 v196, v[2:3]
	v_cvt_pk_bf16_f32 v2, v140, v141
	v_cvt_pk_bf16_f32 v3, v142, v143
	s_waitcnt vmcnt(14)
	ds_write_b64 v197, v[2:3]
	v_cvt_pk_bf16_f32 v2, v132, v133
	v_cvt_pk_bf16_f32 v3, v134, v135
	s_waitcnt vmcnt(13)
	ds_write_b64 v198, v[2:3]
	v_cvt_pk_bf16_f32 v2, v128, v129
	v_cvt_pk_bf16_f32 v3, v130, v131
	s_waitcnt vmcnt(12)
	ds_write_b64 v199, v[2:3]
	v_cvt_pk_bf16_f32 v2, v116, v117
	v_cvt_pk_bf16_f32 v3, v118, v119
	s_waitcnt vmcnt(11)
	ds_write_b64 v200, v[2:3]
	v_cvt_pk_bf16_f32 v2, v108, v109
	s_cmp_lt_u32 s34, 7
	s_cselect_b64 s[6:7], -1, 0
	s_add_i32 s10, s33, -1
	v_cvt_pk_bf16_f32 v3, v110, v111
	s_waitcnt vmcnt(10)
	s_and_b64 s[8:9], s[6:7], exec
	ds_write_b64 v191, v[2:3] offset:256
	s_cselect_b32 s8, s10, 0
	v_readlane_b32 s8, v179, s8
	v_cvt_pk_bf16_f32 v2, v100, v101
	s_cselect_b32 s28, 0x200, 0
	s_ashr_i32 s9, s8, 31
	s_add_u32 s8, s27, s8
	s_addc_u32 s9, s26, s9
	v_cvt_pk_bf16_f32 v3, v102, v103
	s_lshl_b64 s[10:11], s[8:9], 16
	ds_write_b64 v192, v[2:3] offset:256
	v_lshl_add_u64 v[2:3], v[180:181], 0, s[10:11]
	v_mov_b32_e32 v0, s17
	v_cndmask_b32_e64 v3, v0, v3, s[6:7]
	v_mov_b32_e32 v0, s16
	v_cndmask_b32_e64 v2, v0, v2, s[6:7]
	s_lshl_b64 s[8:9], s[8:9], 14
	s_lshl_b32 s56, s28, 4
	v_lshl_add_u64 v[4:5], v[182:183], 0, s[8:9]
	v_lshl_add_u64 v[6:7], v[2:3], 0, s[56:57]
	s_lshl_b32 s8, s28, 5
	s_mov_b32 s9, s57
	global_load_dwordx4 v[168:171], v[2:3], off nt
	global_load_dwordx4 v[164:167], v[6:7], off nt
	v_lshl_add_u64 v[6:7], v[2:3], 0, s[8:9]
	s_mul_i32 s8, s28, 3
	s_lshl_b32 s8, s8, 4
	global_load_dwordx4 v[156:159], v[6:7], off nt
	v_lshl_add_u64 v[6:7], v[2:3], 0, s[8:9]
	s_lshl_b32 s10, s28, 6
	s_mov_b32 s11, s57
	global_load_dwordx4 v[148:151], v[6:7], off nt
	v_lshl_add_u64 v[6:7], v[2:3], 0, s[10:11]
	s_mul_i32 s10, s28, 5
	s_lshl_b32 s35, s28, 1
	s_lshl_b32 s85, s28, 2
	s_lshl_b32 s10, s10, 4
	s_mul_i32 s12, s28, 6
	s_mul_i32 s28, s28, 7
	global_load_dwordx4 v[140:143], v[6:7], off nt
	v_lshl_add_u64 v[6:7], v[2:3], 0, s[10:11]
	s_lshl_b32 s12, s12, 4
	s_mov_b32 s13, s57
	s_lshl_b32 s28, s28, 4
	s_mov_b32 s29, s57
	global_load_dwordx4 v[132:135], v[6:7], off nt
	v_lshl_add_u64 v[6:7], v[2:3], 0, s[12:13]
	v_lshl_add_u64 v[2:3], v[2:3], 0, s[28:29]
	v_mov_b32_e32 v0, s19
	global_load_dwordx4 v[128:131], v[6:7], off nt
	global_load_dwordx4 v[116:119], v[2:3], off nt
	v_cndmask_b32_e64 v3, v0, v5, s[6:7]
	v_mov_b32_e32 v0, s18
	v_cndmask_b32_e64 v2, v0, v4, s[6:7]
	global_load_dwordx4 v[108:111], v[2:3], off nt
	v_lshl_add_u64 v[2:3], v[2:3], 0, s[56:57]
	global_load_dwordx4 v[100:103], v[2:3], off nt
	s_waitcnt lgkmcnt(0)
	s_barrier
	v_mov_b64_e32 v[10:11], v[184:185]
	s_and_saveexec_b64 s[48:49], vcc
	s_cbranch_execz .LBB0_1396
	ds_read_b128 v[2:5], v189
	ds_read_b128 v[6:9], v190
	ds_read_b128 v[204:207], v189 offset:32
	ds_read_b128 v[208:211], v190 offset:32
	ds_read_b128 v[212:215], v189 offset:64
	ds_read_b128 v[216:219], v190 offset:64
	s_waitcnt lgkmcnt(4)
	v_mfma_f32_32x32x16_bf16 v[80:95], v[2:5], v[6:9], 0
	ds_read_b128 v[2:5], v189 offset:96
	ds_read_b128 v[6:9], v190 offset:96
	s_waitcnt lgkmcnt(4)
	v_mfma_f32_32x32x16_bf16 v[80:95], v[204:207], v[208:211], v[80:95]
	ds_read_b128 v[204:207], v189 offset:128
	ds_read_b128 v[208:211], v190 offset:128
	s_waitcnt lgkmcnt(4)
	v_mfma_f32_32x32x16_bf16 v[80:95], v[212:215], v[216:219], v[80:95]
	ds_read_b128 v[212:215], v189 offset:160
	ds_read_b128 v[216:219], v190 offset:160
	s_waitcnt lgkmcnt(4)
	v_mfma_f32_32x32x16_bf16 v[80:95], v[2:5], v[6:9], v[80:95]
	ds_read_b128 v[2:5], v189 offset:192
	ds_read_b128 v[6:9], v190 offset:192
	s_waitcnt lgkmcnt(4)
	v_mfma_f32_32x32x16_bf16 v[80:95], v[204:207], v[208:211], v[80:95]
	ds_read_b128 v[204:207], v189 offset:224
	ds_read_b128 v[208:211], v190 offset:224
	s_waitcnt lgkmcnt(4)
	v_mfma_f32_32x32x16_bf16 v[80:95], v[212:215], v[216:219], v[80:95]
	ds_read_b128 v[212:215], v189 offset:256
	ds_read_b128 v[216:219], v190 offset:256
	s_waitcnt lgkmcnt(4)
	v_mfma_f32_32x32x16_bf16 v[80:95], v[2:5], v[6:9], v[80:95]
	ds_read_b128 v[2:5], v189 offset:288
	ds_read_b128 v[6:9], v190 offset:288
	s_waitcnt lgkmcnt(4)
	v_mfma_f32_32x32x16_bf16 v[80:95], v[204:207], v[208:211], v[80:95]
	s_waitcnt lgkmcnt(2)
	v_mfma_f32_32x32x16_bf16 v[80:95], v[212:215], v[216:219], v[80:95]
	v_mbcnt_lo_u32_b32 v0, -1, 0
	v_mbcnt_hi_u32_b32 v0, -1, v0
	v_mbcnt_lo_u32_b32 v10, -1, 0
	v_mbcnt_hi_u32_b32 v10, -1, v10
	s_nop 0
	v_lshlrev_b32_e32 v0, 2, v0
	v_xor_b32_e32 v0, 0x80, v0
	v_lshlrev_b32_e32 v10, 2, v10
	s_waitcnt lgkmcnt(0)
	v_mfma_f32_32x32x16_bf16 v[80:95], v[2:5], v[6:9], v[80:95]
	s_nop 11
	v_max_f32_e32 v2, v81, v81
	v_max_f32_e32 v3, v80, v80
	v_max_f32_e32 v2, v3, v2
	v_max3_f32 v2, v2, v82, v83
	v_max3_f32 v2, v2, v84, v85
	v_max3_f32 v2, v2, v86, v87
	v_max3_f32 v2, v2, v88, v89
	v_max3_f32 v2, v2, v90, v91
	v_max3_f32 v2, v2, v92, v93
	v_max3_f32 v6, v2, v94, v95
	ds_bpermute_b32 v0, v0, v6
	ds_read_b64_tr_b16 v[2:3], v188
	ds_read_b64_tr_b16 v[4:5], v188 offset:2688
	s_waitcnt lgkmcnt(2)
; DEV unsigned pk2(float lo, float hi) { return (unsigned)f2bf(lo) | ((unsigned)f2bf(hi) << 16); }
; DEV float shfl_xor_(float v, int m) { return __builtin_bit_cast(float, __builtin_amdgcn_ds_bpermute((lane_id() ^ m) << 2, __builtin_bit_cast(int, v))); }
; DEV float fexp2(float x) { return __builtin_amdgcn_exp2f(x); }
; __device__ __forceinline__ s16x4 vtr(lds_cptr p){ return __builtin_bit_cast(s16x4,__builtin_amdgcn_ds_read_tr16_b64_v4i16((__attribute__((address_space(3))) v4i16_t*)p)); }
; DEV void sample_attn_task(int l, int item, int t, LAS unsigned char* sm, unsigned char* ws, const float* cache_ckv, const float* cache_kr, const int* page_table, const float* w_uv) {
;     ...
;         float mx = S[0];
; #pragma unroll
;         for (int r = 1; r < 16; ++r) mx = fmaxf(mx, S[r]);
;         mx = fmaxf(mx, shfl_xor_(mx, 32));
;         const float mn = fmaxf(m, mx), al_ = fexp2(m - mn); float psum = 0.f;
; #pragma unroll
;         for (int r = 0; r < 16; ++r) { S[r] = fexp2(S[r] - mn); psum += S[r]; }
;         psum += shfl_xor_(psum, 32); lsum = lsum * al_ + psum; m = mn;
;         u32x4 pb[2];
; #pragma unroll
;         for (int ks = 0; ks < 2; ++ks) { pb[ks].x = pk2(S[8 * ks + 0], S[8 * ks + 1]); pb[ks].y = pk2(S[8 * ks + 2], S[8 * ks + 3]); pb[ks].z = pk2(S[8 * ks + 4], S[8 * ks + 5]); pb[ks].w = pk2(S[8 * ks + 6], S[8 * ks + 7]); }
; #pragma unroll
;         for (int c = 0; c < 4; ++c) {
; #pragma unroll
;             for (int r = 0; r < 16; ++r) O[c][r] *= al_;
; #pragma unroll
;             for (int ks = 0; ks < 2; ++ks) {
;                 const attn_body::s16x4 lo = attn_body::vtr((attn_body::lds_cptr)(vtb + (16 * ks) * KST + 32 * c)), hi4 = attn_body::vtr((attn_body::lds_cptr)(vtb + (16 * ks + 8) * KST + 32 * c));
;                 const bf16x8 af = {lo[0], lo[1], lo[2], lo[3], hi4[0], hi4[1], hi4[2], hi4[3]};
;                 O[c] = __builtin_amdgcn_mfma_f32_32x32x16_bf16(af, __builtin_bit_cast(bf16x8, pb[ks]), O[c], 0, 0, 0); } }
	v_max3_f32 v11, v185, v6, v0
	v_sub_f32_e32 v6, v80, v11
	v_sub_f32_e32 v7, v81, v11
	v_sub_f32_e32 v8, v82, v11
	v_sub_f32_e32 v9, v83, v11
	v_sub_f32_e32 v12, v84, v11
	v_sub_f32_e32 v14, v86, v11
	v_sub_f32_e32 v13, v85, v11
	v_sub_f32_e32 v15, v87, v11
	v_sub_f32_e32 v80, v88, v11
	v_sub_f32_e32 v81, v89, v11
	v_sub_f32_e32 v83, v91, v11
	v_exp_f32_e32 v6, v6
	v_exp_f32_e32 v7, v7
	v_exp_f32_e32 v8, v8
	v_exp_f32_e32 v88, v9
	v_exp_f32_e32 v89, v12
	v_exp_f32_e32 v91, v14
	v_sub_f32_e32 v82, v90, v11
	v_sub_f32_e32 v84, v92, v11
	v_exp_f32_e32 v90, v13
	v_exp_f32_e32 v92, v15
	v_sub_f32_e32 v0, v185, v11
	v_exp_f32_e32 v0, v0
	v_sub_f32_e32 v85, v93, v11
	v_sub_f32_e32 v86, v94, v11
	v_sub_f32_e32 v87, v95, v11
	v_exp_f32_e32 v93, v80
	v_exp_f32_e32 v94, v81
	v_exp_f32_e32 v95, v82
	v_exp_f32_e32 v185, v83
	v_add_f32_e32 v9, 0, v6
	v_bfe_u32 v14, v88, 16, 1
	v_bfe_u32 v15, v7, 16, 1
	v_bfe_u32 v80, v6, 16, 1
	v_bfe_u32 v81, v8, 16, 1
	v_add_f32_e32 v9, v7, v9
	v_add3_u32 v15, v7, v15, s91
	v_add3_u32 v7, v88, v14, s91
	v_add3_u32 v81, v8, v81, s91
	v_add3_u32 v6, v6, v80, s91
	v_add_f32_e32 v201, v8, v9
	v_lshrrev_b32_e32 v6, 16, v6
	v_lshrrev_b32_e32 v80, 16, v81
	v_pk_mul_f32 v[78:79], v[78:79], v[0:1] op_sel_hi:[1,0]
	v_pk_mul_f32 v[76:77], v[76:77], v[0:1] op_sel_hi:[1,0]
	v_pk_mul_f32 v[74:75], v[74:75], v[0:1] op_sel_hi:[1,0]
	v_pk_mul_f32 v[72:73], v[72:73], v[0:1] op_sel_hi:[1,0]
	v_pk_mul_f32 v[70:71], v[70:71], v[0:1] op_sel_hi:[1,0]
	v_pk_mul_f32 v[68:69], v[68:69], v[0:1] op_sel_hi:[1,0]
	v_pk_mul_f32 v[66:67], v[66:67], v[0:1] op_sel_hi:[1,0]
	v_pk_mul_f32 v[64:65], v[64:65], v[0:1] op_sel_hi:[1,0]
	v_cvt_pk_bf16_f32 v9, v91, v92
	v_cvt_pk_bf16_f32 v8, v89, v90
	v_and_or_b32 v7, v7, s69, v80
	v_and_or_b32 v6, v15, s69, v6
	v_exp_f32_e32 v84, v84
	v_exp_f32_e32 v86, v86
	s_waitcnt lgkmcnt(0)
	v_mfma_f32_32x32x16_bf16 v[64:79], v[2:5], v[6:9], v[64:79]
	v_exp_f32_e32 v85, v85
	v_exp_f32_e32 v87, v87
	ds_read_b64_tr_b16 v[12:13], v188 offset:5376
	ds_read_b64_tr_b16 v[14:15], v188 offset:8064
	v_bfe_u32 v4, v185, 16, 1
	v_bfe_u32 v5, v94, 16, 1
	v_add3_u32 v80, v94, v5, s91
	v_add3_u32 v81, v185, v4, s91
	v_bfe_u32 v4, v93, 16, 1
	v_bfe_u32 v5, v95, 16, 1
	v_add3_u32 v5, v95, v5, s91
	v_add3_u32 v4, v93, v4, s91
	v_lshrrev_b32_e32 v202, 16, v4
	v_lshrrev_b32_e32 v203, 16, v5
	v_cvt_pk_bf16_f32 v5, v86, v87
	v_cvt_pk_bf16_f32 v4, v84, v85
	v_and_or_b32 v3, v81, s69, v203
	v_and_or_b32 v2, v80, s69, v202
	v_pk_mul_f32 v[62:63], v[62:63], v[0:1] op_sel_hi:[1,0]
	v_pk_mul_f32 v[60:61], v[60:61], v[0:1] op_sel_hi:[1,0]
	s_waitcnt lgkmcnt(0)
	v_mfma_f32_32x32x16_bf16 v[64:79], v[12:15], v[2:5], v[64:79]
	ds_read_b64_tr_b16 v[12:13], v188 offset:64
	ds_read_b64_tr_b16 v[14:15], v188 offset:2752
	v_mul_f32_e64 v58, v58, v0
	v_mul_f32_e64 v59, v59, v0
	v_mul_f32_e64 v56, v56, v0
	v_mul_f32_e64 v57, v57, v0
	v_pk_mul_f32 v[54:55], v[54:55], v[0:1] op_sel_hi:[1,0]
	v_pk_mul_f32 v[52:53], v[52:53], v[0:1] op_sel_hi:[1,0]
	v_pk_mul_f32 v[50:51], v[50:51], v[0:1] op_sel_hi:[1,0]
	v_pk_mul_f32 v[48:49], v[48:49], v[0:1] op_sel_hi:[1,0]
	ds_read_b64_tr_b16 v[80:81], v188 offset:5440
	ds_read_b64_tr_b16 v[82:83], v188 offset:8128
	s_waitcnt lgkmcnt(2)
	v_mfma_f32_32x32x16_bf16 v[48:63], v[12:15], v[6:9], v[48:63]
	v_add_f32_e32 v12, v88, v201
	v_add_f32_e32 v12, v89, v12
	v_add_f32_e32 v12, v90, v12
	v_add_f32_e32 v12, v91, v12
	v_add_f32_e32 v12, v92, v12
	v_add_f32_e32 v12, v93, v12
	v_add_f32_e32 v88, v94, v12
	ds_read_b64_tr_b16 v[12:13], v188 offset:128
	ds_read_b64_tr_b16 v[14:15], v188 offset:2816
	v_pk_mul_f32 v[46:47], v[46:47], v[0:1] op_sel_hi:[1,0]
	v_pk_mul_f32 v[44:45], v[44:45], v[0:1] op_sel_hi:[1,0]
	v_pk_mul_f32 v[42:43], v[42:43], v[0:1] op_sel_hi:[1,0]
	v_pk_mul_f32 v[40:41], v[40:41], v[0:1] op_sel_hi:[1,0]
	v_pk_mul_f32 v[38:39], v[38:39], v[0:1] op_sel_hi:[1,0]
	v_pk_mul_f32 v[36:37], v[36:37], v[0:1] op_sel_hi:[1,0]
	v_pk_mul_f32 v[34:35], v[34:35], v[0:1] op_sel_hi:[1,0]
	v_pk_mul_f32 v[32:33], v[32:33], v[0:1] op_sel_hi:[1,0]
	s_waitcnt lgkmcnt(2)
	v_mfma_f32_32x32x16_bf16 v[48:63], v[80:83], v[2:5], v[48:63]
	ds_read_b64_tr_b16 v[80:81], v188 offset:5504
	ds_read_b64_tr_b16 v[82:83], v188 offset:8192
	v_mul_f32_e64 v30, v30, v0
	v_mul_f32_e64 v31, v31, v0
	v_mul_f32_e64 v28, v28, v0
	v_mul_f32_e64 v29, v29, v0
	v_pk_mul_f32 v[26:27], v[26:27], v[0:1] op_sel_hi:[1,0]
	v_pk_mul_f32 v[24:25], v[24:25], v[0:1] op_sel_hi:[1,0]
	v_pk_mul_f32 v[22:23], v[22:23], v[0:1] op_sel_hi:[1,0]
	v_pk_mul_f32 v[20:21], v[20:21], v[0:1] op_sel_hi:[1,0]
	s_waitcnt lgkmcnt(2)
	v_mfma_f32_32x32x16_bf16 v[32:47], v[12:15], v[6:9], v[32:47]
	v_add_f32_e32 v12, v95, v88
	v_add_f32_e32 v12, v185, v12
	v_add_f32_e32 v12, v84, v12
	v_add_f32_e32 v12, v85, v12
	v_add_f32_e32 v12, v86, v12
	v_add_f32_e32 v84, v87, v12
	ds_read_b64_tr_b16 v[12:13], v188 offset:192
	ds_read_b64_tr_b16 v[14:15], v188 offset:2880
	v_pk_mul_f32 v[18:19], v[18:19], v[0:1] op_sel_hi:[1,0]
	v_pk_mul_f32 v[16:17], v[16:17], v[0:1] op_sel_hi:[1,0]
	s_waitcnt lgkmcnt(2)
	v_mfma_f32_32x32x16_bf16 v[32:47], v[80:83], v[2:5], v[32:47]
	ds_read_b64_tr_b16 v[80:81], v188 offset:5568
	ds_read_b64_tr_b16 v[82:83], v188 offset:8256
	v_mov_b32_e32 v185, v11
	s_waitcnt lgkmcnt(2)
	v_mfma_f32_32x32x16_bf16 v[16:31], v[12:15], v[6:9], v[16:31]
	v_xor_b32_e32 v6, 0x80, v10
	ds_bpermute_b32 v6, v6, v84
	s_waitcnt lgkmcnt(0)
	v_add_f32_e32 v10, v84, v6
	v_mfma_f32_32x32x16_bf16 v[16:31], v[80:83], v[2:5], v[16:31]
	v_fmac_f32_e32 v10, v184, v0
	v_mov_b32_e32 v184, v10
; DEV unsigned pk2(float lo, float hi) { return (unsigned)f2bf(lo) | ((unsigned)f2bf(hi) << 16); }
; DEV void lds_barrier() { asm volatile("s_waitcnt lgkmcnt(0)" ::: "memory"); __builtin_amdgcn_s_barrier(); asm volatile("" ::: "memory"); }
; #define LAS __attribute__((address_space(3)))
; DEV void sample_attn_task(int l, int item, int t, LAS unsigned char* sm, unsigned char* ws, const float* cache_ckv, const float* cache_kr, const int* page_table, const float* w_uv) {
;     ...
;       for (int pg = 0; pg < 2; ++pg) {
; #pragma unroll
;         for (int i = 0; i < 8; ++i) { const int e = t + 512 * i, key = e >> 5, c4 = e & 31; const f32x4 v = pk[8 * pg + i]; u32x2 w; w.x = pk2(v[0], v[1]); w.y = pk2(v[2], v[3]); *(LAS u32x2*)(KB + (128 * pg + key) * KST + 4 * c4) = w; }
; #pragma unroll
;         for (int i = 0; i < 2; ++i) { const int e = t + 512 * i, key = e >> 3, c4 = e & 7; const f32x4 v = pr[2 * pg + i]; u32x2 w; w.x = pk2(v[0], v[1]); w.y = pk2(v[2], v[3]); *(LAS u32x2*)(KB + (128 * pg + key) * KST + 128 + 4 * c4) = w; }
;         LOAD_PAGE(pg, 2 * it + pg + 2);
;         lds_barrier();
;         if ((wv >> 2) == pg) {
;         f32x16 S;
; #pragma unroll
;         for (int r = 0; r < 16; ++r) S[r] = 0.f;
;         const LAS bf16_t* kr_ = KB + (32 * wv + r32) * KST + 8 * hi;
; #pragma unroll
;         for (int s2 = 0; s2 < 10; ++s2) S = __builtin_amdgcn_mfma_f32_32x32x16_bf16(*(const LAS bf16x8*)(kr_ + 16 * s2), *(const LAS bf16x8*)(QB + r32 * KST + 8 * hi + 16 * s2), S, 0, 0, 0);
.LBB0_1396:
	s_or_b64 exec, exec, s[48:49]
	s_waitcnt vmcnt(19)
	v_cvt_pk_bf16_f32 v2, v172, v173
	v_cvt_pk_bf16_f32 v3, v174, v175
	s_waitcnt vmcnt(18)
	ds_write_b64 v193, v[2:3] offset:43008
	v_cvt_pk_bf16_f32 v2, v160, v161
	v_cvt_pk_bf16_f32 v3, v162, v163
	s_waitcnt vmcnt(17)
	ds_write_b64 v194, v[2:3] offset:43008
	v_cvt_pk_bf16_f32 v2, v152, v153
	v_cvt_pk_bf16_f32 v3, v154, v155
	s_waitcnt vmcnt(16)
	ds_write_b64 v195, v[2:3] offset:43008
	v_cvt_pk_bf16_f32 v2, v144, v145
	v_cvt_pk_bf16_f32 v3, v146, v147
	s_waitcnt vmcnt(15)
	ds_write_b64 v196, v[2:3] offset:43008
	v_cvt_pk_bf16_f32 v2, v136, v137
	v_cvt_pk_bf16_f32 v3, v138, v139
	s_waitcnt vmcnt(14)
	ds_write_b64 v197, v[2:3] offset:43008
	v_cvt_pk_bf16_f32 v2, v124, v125
	v_cvt_pk_bf16_f32 v3, v126, v127
	s_waitcnt vmcnt(13)
	ds_write_b64 v198, v[2:3] offset:43008
	v_cvt_pk_bf16_f32 v2, v120, v121
	v_cvt_pk_bf16_f32 v3, v122, v123
	s_waitcnt vmcnt(12)
	ds_write_b64 v199, v[2:3] offset:43008
	v_cvt_pk_bf16_f32 v2, v112, v113
	v_cvt_pk_bf16_f32 v3, v114, v115
	s_waitcnt vmcnt(11)
	ds_write_b64 v200, v[2:3] offset:43008
	v_cvt_pk_bf16_f32 v2, v104, v105
	v_cvt_pk_bf16_f32 v3, v106, v107
	s_waitcnt vmcnt(10)
	s_and_b64 s[48:49], s[6:7], exec
	ds_write_b64 v191, v[2:3] offset:43264
	s_cselect_b32 s48, s33, 0
	v_readlane_b32 s48, v179, s48
	v_cvt_pk_bf16_f32 v2, v96, v97
	s_ashr_i32 s49, s48, 31
	s_add_u32 s48, s27, s48
	s_addc_u32 s49, s26, s49
	v_cvt_pk_bf16_f32 v3, v98, v99
	s_lshl_b64 s[92:93], s[48:49], 16
	ds_write_b64 v192, v[2:3] offset:43264
	v_lshl_add_u64 v[2:3], v[180:181], 0, s[92:93]
	v_mov_b32_e32 v0, s17
	v_cndmask_b32_e64 v3, v0, v3, s[6:7]
	v_mov_b32_e32 v0, s16
	v_cndmask_b32_e64 v2, v0, v2, s[6:7]
	s_lshl_b64 s[48:49], s[48:49], 14
	v_lshl_add_u64 v[4:5], v[182:183], 0, s[48:49]
	v_lshl_add_u64 v[6:7], v[2:3], 0, s[56:57]
	s_lshl_b32 s48, s35, 4
	s_mov_b32 s49, s57
	global_load_dwordx4 v[172:175], v[2:3], off nt
	global_load_dwordx4 v[160:163], v[6:7], off nt
	v_lshl_add_u64 v[6:7], v[2:3], 0, s[48:49]
	global_load_dwordx4 v[152:155], v[6:7], off nt
	v_lshl_add_u64 v[6:7], v[2:3], 0, s[8:9]
	s_lshl_b32 s8, s85, 4
	s_mov_b32 s9, s57
	global_load_dwordx4 v[144:147], v[6:7], off nt
	v_lshl_add_u64 v[6:7], v[2:3], 0, s[8:9]
	global_load_dwordx4 v[136:139], v[6:7], off nt
	v_lshl_add_u64 v[6:7], v[2:3], 0, s[10:11]
	global_load_dwordx4 v[124:127], v[6:7], off nt
	v_lshl_add_u64 v[6:7], v[2:3], 0, s[12:13]
	v_lshl_add_u64 v[2:3], v[2:3], 0, s[28:29]
	v_mov_b32_e32 v0, s19
	global_load_dwordx4 v[120:123], v[6:7], off nt
	global_load_dwordx4 v[112:115], v[2:3], off nt
	v_cndmask_b32_e64 v3, v0, v5, s[6:7]
	v_mov_b32_e32 v0, s18
	v_cndmask_b32_e64 v2, v0, v4, s[6:7]
	global_load_dwordx4 v[104:107], v[2:3], off nt
	v_lshl_add_u64 v[2:3], v[2:3], 0, s[56:57]
	global_load_dwordx4 v[96:99], v[2:3], off nt
	s_waitcnt lgkmcnt(0)
	s_barrier
	s_and_saveexec_b64 s[6:7], s[4:5]
	s_cbranch_execz .LBB0_1393
	ds_read_b128 v[2:5], v189
	ds_read_b128 v[6:9], v190
	ds_read_b128 v[204:207], v189 offset:32
	ds_read_b128 v[208:211], v190 offset:32
	ds_read_b128 v[212:215], v189 offset:64
	ds_read_b128 v[216:219], v190 offset:64
	s_waitcnt lgkmcnt(4)
	v_mfma_f32_32x32x16_bf16 v[80:95], v[2:5], v[6:9], 0
	ds_read_b128 v[2:5], v189 offset:96
	ds_read_b128 v[6:9], v190 offset:96
	s_waitcnt lgkmcnt(4)
	v_mfma_f32_32x32x16_bf16 v[80:95], v[204:207], v[208:211], v[80:95]
	ds_read_b128 v[204:207], v189 offset:128
	ds_read_b128 v[208:211], v190 offset:128
	s_waitcnt lgkmcnt(4)
	v_mfma_f32_32x32x16_bf16 v[80:95], v[212:215], v[216:219], v[80:95]
	ds_read_b128 v[212:215], v189 offset:160
	ds_read_b128 v[216:219], v190 offset:160
	s_waitcnt lgkmcnt(4)
	v_mfma_f32_32x32x16_bf16 v[80:95], v[2:5], v[6:9], v[80:95]
	ds_read_b128 v[2:5], v189 offset:192
	ds_read_b128 v[6:9], v190 offset:192
	s_waitcnt lgkmcnt(4)
	v_mfma_f32_32x32x16_bf16 v[80:95], v[204:207], v[208:211], v[80:95]
	ds_read_b128 v[204:207], v189 offset:224
	ds_read_b128 v[208:211], v190 offset:224
	s_waitcnt lgkmcnt(4)
	v_mfma_f32_32x32x16_bf16 v[80:95], v[212:215], v[216:219], v[80:95]
	ds_read_b128 v[212:215], v189 offset:256
	ds_read_b128 v[216:219], v190 offset:256
	s_waitcnt lgkmcnt(4)
	v_mfma_f32_32x32x16_bf16 v[80:95], v[2:5], v[6:9], v[80:95]
	ds_read_b128 v[2:5], v189 offset:288
	ds_read_b128 v[6:9], v190 offset:288
	s_waitcnt lgkmcnt(4)
	v_mfma_f32_32x32x16_bf16 v[80:95], v[204:207], v[208:211], v[80:95]
	s_waitcnt lgkmcnt(2)
	v_mfma_f32_32x32x16_bf16 v[80:95], v[212:215], v[216:219], v[80:95]
	v_mbcnt_lo_u32_b32 v0, -1, 0
	v_mbcnt_hi_u32_b32 v0, -1, v0
	v_mbcnt_lo_u32_b32 v10, -1, 0
	v_mbcnt_hi_u32_b32 v10, -1, v10
	s_nop 0
	v_lshlrev_b32_e32 v0, 2, v0
	v_xor_b32_e32 v0, 0x80, v0
	v_lshlrev_b32_e32 v10, 2, v10
	s_waitcnt lgkmcnt(0)
	v_mfma_f32_32x32x16_bf16 v[80:95], v[2:5], v[6:9], v[80:95]
	s_nop 11
	v_max_f32_e32 v2, v81, v81
	v_max_f32_e32 v3, v80, v80
	v_max_f32_e32 v2, v3, v2
	v_max3_f32 v2, v2, v82, v83
	v_max3_f32 v2, v2, v84, v85
	v_max3_f32 v2, v2, v86, v87
	v_max3_f32 v2, v2, v88, v89
	v_max3_f32 v2, v2, v90, v91
	v_max3_f32 v2, v2, v92, v93
	v_max3_f32 v6, v2, v94, v95
	ds_bpermute_b32 v0, v0, v6
	ds_read_b64_tr_b16 v[2:3], v188
	ds_read_b64_tr_b16 v[4:5], v188 offset:2688
	s_waitcnt lgkmcnt(2)
; DEV unsigned pk2(float lo, float hi) { return (unsigned)f2bf(lo) | ((unsigned)f2bf(hi) << 16); }
; DEV float shfl_xor_(float v, int m) { return __builtin_bit_cast(float, __builtin_amdgcn_ds_bpermute((lane_id() ^ m) << 2, __builtin_bit_cast(int, v))); }
; DEV float fexp2(float x) { return __builtin_amdgcn_exp2f(x); }
; __device__ __forceinline__ s16x4 vtr(lds_cptr p){ return __builtin_bit_cast(s16x4,__builtin_amdgcn_ds_read_tr16_b64_v4i16((__attribute__((address_space(3))) v4i16_t*)p)); }
; DEV void sample_attn_task(int l, int item, int t, LAS unsigned char* sm, unsigned char* ws, const float* cache_ckv, const float* cache_kr, const int* page_table, const float* w_uv) {
;     ...
;         float mx = S[0];
; #pragma unroll
;         for (int r = 1; r < 16; ++r) mx = fmaxf(mx, S[r]);
;         mx = fmaxf(mx, shfl_xor_(mx, 32));
;         const float mn = fmaxf(m, mx), al_ = fexp2(m - mn); float psum = 0.f;
; #pragma unroll
;         for (int r = 0; r < 16; ++r) { S[r] = fexp2(S[r] - mn); psum += S[r]; }
;         psum += shfl_xor_(psum, 32); lsum = lsum * al_ + psum; m = mn;
;         u32x4 pb[2];
; #pragma unroll
;         for (int ks = 0; ks < 2; ++ks) { pb[ks].x = pk2(S[8 * ks + 0], S[8 * ks + 1]); pb[ks].y = pk2(S[8 * ks + 2], S[8 * ks + 3]); pb[ks].z = pk2(S[8 * ks + 4], S[8 * ks + 5]); pb[ks].w = pk2(S[8 * ks + 6], S[8 * ks + 7]); }
; #pragma unroll
;         for (int c = 0; c < 4; ++c) {
; #pragma unroll
;             for (int r = 0; r < 16; ++r) O[c][r] *= al_;
; #pragma unroll
;             for (int ks = 0; ks < 2; ++ks) {
;                 const attn_body::s16x4 lo = attn_body::vtr((attn_body::lds_cptr)(vtb + (16 * ks) * KST + 32 * c)), hi4 = attn_body::vtr((attn_body::lds_cptr)(vtb + (16 * ks + 8) * KST + 32 * c));
;                 const bf16x8 af = {lo[0], lo[1], lo[2], lo[3], hi4[0], hi4[1], hi4[2], hi4[3]};
;                 O[c] = __builtin_amdgcn_mfma_f32_32x32x16_bf16(af, __builtin_bit_cast(bf16x8, pb[ks]), O[c], 0, 0, 0); } }
	v_max3_f32 v11, v185, v6, v0
	v_sub_f32_e32 v6, v80, v11
	v_sub_f32_e32 v7, v81, v11
	v_sub_f32_e32 v8, v82, v11
	v_sub_f32_e32 v9, v83, v11
	v_sub_f32_e32 v12, v84, v11
	v_sub_f32_e32 v14, v86, v11
	v_sub_f32_e32 v13, v85, v11
	v_sub_f32_e32 v15, v87, v11
	v_sub_f32_e32 v80, v88, v11
	v_sub_f32_e32 v81, v89, v11
	v_sub_f32_e32 v83, v91, v11
	v_exp_f32_e32 v6, v6
	v_exp_f32_e32 v7, v7
	v_exp_f32_e32 v8, v8
	v_exp_f32_e32 v88, v9
	v_exp_f32_e32 v89, v12
	v_exp_f32_e32 v91, v14
	v_sub_f32_e32 v82, v90, v11
	v_sub_f32_e32 v84, v92, v11
	v_exp_f32_e32 v90, v13
	v_exp_f32_e32 v92, v15
	v_sub_f32_e32 v0, v185, v11
	v_exp_f32_e32 v0, v0
	v_sub_f32_e32 v85, v93, v11
	v_sub_f32_e32 v86, v94, v11
	v_sub_f32_e32 v87, v95, v11
	v_exp_f32_e32 v93, v80
	v_exp_f32_e32 v94, v81
	v_exp_f32_e32 v95, v82
	v_exp_f32_e32 v185, v83
	v_add_f32_e32 v9, 0, v6
	v_bfe_u32 v14, v88, 16, 1
	v_bfe_u32 v15, v7, 16, 1
	v_bfe_u32 v80, v6, 16, 1
	v_bfe_u32 v81, v8, 16, 1
	v_add_f32_e32 v9, v7, v9
	v_add3_u32 v15, v7, v15, s91
	v_add3_u32 v7, v88, v14, s91
	v_add3_u32 v81, v8, v81, s91
	v_add3_u32 v6, v6, v80, s91
	v_add_f32_e32 v201, v8, v9
	v_lshrrev_b32_e32 v6, 16, v6
	v_lshrrev_b32_e32 v80, 16, v81
	v_pk_mul_f32 v[78:79], v[78:79], v[0:1] op_sel_hi:[1,0]
	v_pk_mul_f32 v[76:77], v[76:77], v[0:1] op_sel_hi:[1,0]
	v_pk_mul_f32 v[74:75], v[74:75], v[0:1] op_sel_hi:[1,0]
	v_pk_mul_f32 v[72:73], v[72:73], v[0:1] op_sel_hi:[1,0]
	v_pk_mul_f32 v[70:71], v[70:71], v[0:1] op_sel_hi:[1,0]
	v_pk_mul_f32 v[68:69], v[68:69], v[0:1] op_sel_hi:[1,0]
	v_pk_mul_f32 v[66:67], v[66:67], v[0:1] op_sel_hi:[1,0]
	v_pk_mul_f32 v[64:65], v[64:65], v[0:1] op_sel_hi:[1,0]
	v_cvt_pk_bf16_f32 v9, v91, v92
	v_cvt_pk_bf16_f32 v8, v89, v90
	v_and_or_b32 v7, v7, s69, v80
	v_and_or_b32 v6, v15, s69, v6
	v_exp_f32_e32 v84, v84
	v_exp_f32_e32 v86, v86
	s_waitcnt lgkmcnt(0)
	v_mfma_f32_32x32x16_bf16 v[64:79], v[2:5], v[6:9], v[64:79]
	v_exp_f32_e32 v85, v85
	v_exp_f32_e32 v87, v87
	ds_read_b64_tr_b16 v[12:13], v188 offset:5376
	ds_read_b64_tr_b16 v[14:15], v188 offset:8064
	v_bfe_u32 v4, v185, 16, 1
	v_bfe_u32 v5, v94, 16, 1
	v_add3_u32 v80, v94, v5, s91
	v_add3_u32 v81, v185, v4, s91
	v_bfe_u32 v4, v93, 16, 1
	v_bfe_u32 v5, v95, 16, 1
	v_add3_u32 v5, v95, v5, s91
	v_add3_u32 v4, v93, v4, s91
	v_lshrrev_b32_e32 v202, 16, v4
	v_lshrrev_b32_e32 v203, 16, v5
	v_cvt_pk_bf16_f32 v5, v86, v87
	v_cvt_pk_bf16_f32 v4, v84, v85
	v_and_or_b32 v3, v81, s69, v203
	v_and_or_b32 v2, v80, s69, v202
	v_pk_mul_f32 v[62:63], v[62:63], v[0:1] op_sel_hi:[1,0]
	v_pk_mul_f32 v[60:61], v[60:61], v[0:1] op_sel_hi:[1,0]
	s_waitcnt lgkmcnt(0)
	v_mfma_f32_32x32x16_bf16 v[64:79], v[12:15], v[2:5], v[64:79]
	ds_read_b64_tr_b16 v[12:13], v188 offset:64
	ds_read_b64_tr_b16 v[14:15], v188 offset:2752
	v_mul_f32_e64 v58, v58, v0
	v_mul_f32_e64 v59, v59, v0
	v_mul_f32_e64 v56, v56, v0
	v_mul_f32_e64 v57, v57, v0
	v_pk_mul_f32 v[54:55], v[54:55], v[0:1] op_sel_hi:[1,0]
	v_pk_mul_f32 v[52:53], v[52:53], v[0:1] op_sel_hi:[1,0]
	v_pk_mul_f32 v[50:51], v[50:51], v[0:1] op_sel_hi:[1,0]
	v_pk_mul_f32 v[48:49], v[48:49], v[0:1] op_sel_hi:[1,0]
	ds_read_b64_tr_b16 v[80:81], v188 offset:5440
	ds_read_b64_tr_b16 v[82:83], v188 offset:8128
	s_waitcnt lgkmcnt(2)
	v_mfma_f32_32x32x16_bf16 v[48:63], v[12:15], v[6:9], v[48:63]
	v_add_f32_e32 v12, v88, v201
	v_add_f32_e32 v12, v89, v12
	v_add_f32_e32 v12, v90, v12
	v_add_f32_e32 v12, v91, v12
	v_add_f32_e32 v12, v92, v12
	v_add_f32_e32 v12, v93, v12
	v_add_f32_e32 v88, v94, v12
	ds_read_b64_tr_b16 v[12:13], v188 offset:128
	ds_read_b64_tr_b16 v[14:15], v188 offset:2816
	v_pk_mul_f32 v[46:47], v[46:47], v[0:1] op_sel_hi:[1,0]
	v_pk_mul_f32 v[44:45], v[44:45], v[0:1] op_sel_hi:[1,0]
	v_pk_mul_f32 v[42:43], v[42:43], v[0:1] op_sel_hi:[1,0]
	v_pk_mul_f32 v[40:41], v[40:41], v[0:1] op_sel_hi:[1,0]
	v_pk_mul_f32 v[38:39], v[38:39], v[0:1] op_sel_hi:[1,0]
	v_pk_mul_f32 v[36:37], v[36:37], v[0:1] op_sel_hi:[1,0]
	v_pk_mul_f32 v[34:35], v[34:35], v[0:1] op_sel_hi:[1,0]
	v_pk_mul_f32 v[32:33], v[32:33], v[0:1] op_sel_hi:[1,0]
	s_waitcnt lgkmcnt(2)
	v_mfma_f32_32x32x16_bf16 v[48:63], v[80:83], v[2:5], v[48:63]
	ds_read_b64_tr_b16 v[80:81], v188 offset:5504
	ds_read_b64_tr_b16 v[82:83], v188 offset:8192
	v_mul_f32_e64 v30, v30, v0
	v_mul_f32_e64 v31, v31, v0
	v_mul_f32_e64 v28, v28, v0
	v_mul_f32_e64 v29, v29, v0
	v_pk_mul_f32 v[26:27], v[26:27], v[0:1] op_sel_hi:[1,0]
	v_pk_mul_f32 v[24:25], v[24:25], v[0:1] op_sel_hi:[1,0]
	v_pk_mul_f32 v[22:23], v[22:23], v[0:1] op_sel_hi:[1,0]
	v_pk_mul_f32 v[20:21], v[20:21], v[0:1] op_sel_hi:[1,0]
	s_waitcnt lgkmcnt(2)
	v_mfma_f32_32x32x16_bf16 v[32:47], v[12:15], v[6:9], v[32:47]
	v_add_f32_e32 v12, v95, v88
	v_add_f32_e32 v12, v185, v12
	v_add_f32_e32 v12, v84, v12
	v_add_f32_e32 v12, v85, v12
	v_add_f32_e32 v12, v86, v12
	v_add_f32_e32 v84, v87, v12
	ds_read_b64_tr_b16 v[12:13], v188 offset:192
	ds_read_b64_tr_b16 v[14:15], v188 offset:2880
	v_pk_mul_f32 v[18:19], v[18:19], v[0:1] op_sel_hi:[1,0]
	v_pk_mul_f32 v[16:17], v[16:17], v[0:1] op_sel_hi:[1,0]
	s_waitcnt lgkmcnt(2)
	v_mfma_f32_32x32x16_bf16 v[32:47], v[80:83], v[2:5], v[32:47]
	ds_read_b64_tr_b16 v[80:81], v188 offset:5568
	ds_read_b64_tr_b16 v[82:83], v188 offset:8256
	v_mov_b32_e32 v185, v11
	s_waitcnt lgkmcnt(2)
	v_mfma_f32_32x32x16_bf16 v[16:31], v[12:15], v[6:9], v[16:31]
	v_xor_b32_e32 v6, 0x80, v10
	ds_bpermute_b32 v6, v6, v84
	s_waitcnt lgkmcnt(0)
	v_add_f32_e32 v10, v84, v6
	v_mfma_f32_32x32x16_bf16 v[16:31], v[80:83], v[2:5], v[16:31]
	v_fmac_f32_e32 v10, v184, v0
	v_mov_b32_e32 v184, v10
	s_branch .LBB0_1393
